# fewer-ops stack: combo + rstd reused across a workgroup's M1 tiles + S5 Y-store address stepping
# speedup vs baseline: 1.0084x; 1.0029x over previous
.LBB0_1294:
	v_readlane_b32 s12, v255, 44
	s_lshl_b32 s12, s12, 1
	v_readlane_b32 s13, v255, 45
	s_or_b32 s96, s12, 1
	s_lshl_b64 s[12:13], s[96:97], 16
	v_readlane_b32 s14, v254, 11
	s_add_u32 s12, s14, s12
	v_readlane_b32 s14, v254, 14
	s_addc_u32 s13, s14, s13
	s_mul_i32 s15, s96, 0x1e000
	v_readlane_b32 s19, v254, 7
	s_mul_hi_u32 s14, s96, 0x1e000
	s_add_u32 s51, s19, s15
	v_readlane_b32 s15, v254, 8
	s_addc_u32 s76, s15, s14
	s_add_u32 s14, s6, 0x9900000
	s_addc_u32 s15, s7, 0
	s_lshl_b32 s6, s18, 5
	s_and_b32 s18, s6, 0x60
	s_add_i32 m0, s37, 0x18000
	v_lshl_add_u64 v[6:7], v[6:7], 0, s[20:21]
	s_lshl_b32 s19, s17, 13
	s_lshl_b32 s22, s18, 7
	s_waitcnt vmcnt(2)
	s_barrier
	global_load_lds_dwordx4 v[6:7], off
	v_lshl_add_u64 v[4:5], v[4:5], 0, s[20:21]
	s_add_i32 m0, s37, 0x1a000
	s_add_i32 s77, s37, 0x8000
	s_add_i32 s78, s37, 0xa000
	global_load_lds_dwordx4 v[4:5], off
	v_lshl_add_u64 v[0:1], v[0:1], 0, s[20:21]
	s_mov_b32 m0, s77
	s_add_u32 s6, s52, 0x40080
	global_load_lds_dwordx4 v[0:1], off
	v_lshl_add_u64 v[0:1], v[2:3], 0, s[20:21]
	s_mov_b32 m0, s78
	s_addc_u32 s7, s53, 0
	global_load_lds_dwordx4 v[0:1], off
	s_add_i32 m0, s37, 0x1c000
	v_lshl_add_u64 v[0:1], s[6:7], 0, v[200:201]
	global_load_lds_dwordx4 v[0:1], off
	v_lshl_add_u64 v[0:1], s[6:7], 0, v[144:145]
	s_add_i32 m0, s37, 0x1e000
	s_cmpk_lt_u32 s16, 0x100
	global_load_lds_dwordx4 v[0:1], off
	v_lshrrev_b32_e32 v1, 1, v8
	v_and_b32_e32 v1, 24, v1
	v_and_b32_e32 v0, 15, v8
	v_lshlrev_b32_e32 v2, 1, v1
	v_lshl_or_b32 v162, s17, 6, v0
	v_lshl_or_b32 v0, v0, 6, v2
	v_lshlrev_b32_e32 v2, 2, v8
	v_and_b32_e32 v2, 32, v2
	v_bitop3_b32 v3, v0, s19, v2 bitop3:0xde
	v_bitop3_b32 v163, s22, v0, v2 bitop3:0xf6
	v_lshlrev_b32_e32 v0, 14, v13
	v_and_b32_e32 v0, 0xffff8000, v0
	v_or_b32_e32 v164, s18, v1
	v_lshl_add_u32 v0, v12, 11, v0
	v_and_b32_e32 v1, 1, v13
	v_lshl_or_b32 v0, v1, 6, v0
	v_lshl_add_u32 v150, v14, 1, v0
	v_lshlrev_b32_e32 v0, 14, v9
	v_and_b32_e32 v0, 0xffff8000, v0
	s_waitcnt vmcnt(6)
	v_lshl_add_u32 v0, v10, 11, v0
	v_and_b32_e32 v1, 1, v9
	v_lshl_or_b32 v0, v1, 6, v0
	v_readlane_b32 s6, v255, 14
	s_cselect_b64 s[16:17], -1, 0
	v_mov_b32_e32 v151, v201
	v_lshl_add_u32 v152, v11, 1, v0
	v_mov_b32_e32 v153, v201
	s_mov_b32 s79, 0
	v_add_u32_e32 v165, 0, v3
	v_readlane_b32 s41, v254, 56
	s_mov_b32 s40, s6
	s_barrier
	v_readlane_b32 s7, v255, 15
	s_lshl_b32 s92, s40, 8
	s_add_i32 s94, s92, 0xffffe000
	s_lshr_b32 s94, s94, 11
	s_add_i32 s94, s94, 1
	s_cmp_gt_i32 s40, 31
	s_cselect_b32 s94, s94, 0
	s_mul_hi_u32 s95, s94, 0x6000
	s_mulk_i32 s94, 0x6000
	v_lshl_or_b32 v226, s41, 8, v164
	s_add_u32 s94, s51, s94
	v_add_u32_e32 v188, s92, v162
	s_addc_u32 s95, s76, s95
	v_ashrrev_i32_e32 v227, 31, v226
	v_ashrrev_i32_e32 v189, 31, v188
	v_lshl_add_u64 v[226:227], v[226:227], 2, s[94:95]
	v_lshl_add_u64 v[188:189], v[188:189], 2, s[12:13]
	global_load_dwordx4 v[218:221], v[226:227], off offset:16
	global_load_dwordx4 v[222:225], v[226:227], off
	global_load_dwordx4 v[230:233], v[226:227], off offset:528
	global_load_dwordx4 v[238:241], v[226:227], off offset:512
	s_mov_b32 s87, -1
	s_branch .LBB0_1297

.LBB0_1307:
	s_lshl_b32 s19, s40, 8
	s_add_i32 s8, s19, 0xffffe000
	s_lshr_b32 s8, s8, 11
	s_add_i32 s8, s8, 1
	s_cmp_gt_i32 s40, 31
	s_cselect_b32 s8, s8, 0
	s_mul_hi_u32 s9, s8, 0x6000
	s_mulk_i32 s8, 0x6000
	v_lshl_or_b32 v154, s41, 8, v164
	s_add_u32 s8, s51, s8
	v_add_u32_e32 v158, s19, v162
	s_addc_u32 s9, s76, s9
	v_ashrrev_i32_e32 v155, 31, v154
	v_ashrrev_i32_e32 v159, 31, v158
	v_lshl_add_u64 v[84:85], v[154:155], 2, s[8:9]
	v_lshl_add_u64 v[174:175], v[158:159], 2, s[12:13]
	v_mov_b32_e32 v88, v218
	v_mov_b32_e32 v89, v219
	v_mov_b32_e32 v90, v220
	v_mov_b32_e32 v91, v221
	v_mov_b32_e32 v92, v222
	v_mov_b32_e32 v93, v223
	v_mov_b32_e32 v94, v224
	v_mov_b32_e32 v95, v225
	v_mov_b32_e32 v80, v230
	v_mov_b32_e32 v81, v231
	v_mov_b32_e32 v82, v232
	v_mov_b32_e32 v83, v233
	s_nop 0
	v_mov_b32_e32 v84, v238
	v_mov_b32_e32 v85, v239
	v_mov_b32_e32 v86, v240
	v_mov_b32_e32 v87, v241
	v_or_b32_e32 v176, 16, v158
	s_cmp_eq_u32 s40, s87
	s_cselect_b32 s89, 1, 0
	s_cbranch_scc1 .Lru_have
	global_load_dword v242, v[174:175], off
	global_load_dword v243, v[174:175], off offset:64
	global_load_dword v244, v[174:175], off offset:128
	global_load_dword v245, v[174:175], off offset:192
	global_load_dword v246, v[174:175], off offset:512
	global_load_dword v247, v[174:175], off offset:576
	global_load_dword v248, v[174:175], off offset:640
	global_load_dword v249, v[174:175], off offset:704
	s_waitcnt vmcnt(0)
.Lru_have:
	v_mov_b32_e32 v173, v242
	v_mov_b32_e32 v172, v243
	v_mov_b32_e32 v171, v244
	v_or_b32_e32 v160, 32, v158
	v_or_b32_e32 v156, 48, v158
	v_lshlrev_b64 v[158:159], 13, v[158:159]
	v_mov_b32_e32 v170, v245
	v_mov_b32_e32 v169, v246
	v_mov_b32_e32 v168, v247
	v_mov_b32_e32 v167, v248
	v_mov_b32_e32 v166, v249
	v_lshl_add_u64 v[174:175], s[14:15], 0, v[158:159]
	v_lshlrev_b64 v[158:159], 1, v[154:155]
	v_lshl_add_u64 v[154:155], v[174:175], 0, v[158:159]
	v_ashrrev_i32_e32 v177, 31, v176
	v_ashrrev_i32_e32 v161, 31, v160
	v_ashrrev_i32_e32 v157, 31, v156
	s_waitcnt vmcnt(16)
	s_cmp_lg_u64 s[6:7], 0
	s_cbranch_scc0 .Lpf_skip
	s_lshl_b32 s92, s22, 8
	s_add_i32 s94, s92, 0xffffe000
	s_lshr_b32 s94, s94, 11
	s_add_i32 s94, s94, 1
	s_cmp_gt_i32 s22, 31
	s_cselect_b32 s94, s94, 0
	s_mul_hi_u32 s95, s94, 0x6000
	s_mulk_i32 s94, 0x6000
	v_lshl_or_b32 v226, s18, 8, v164
	s_add_u32 s94, s51, s94
	v_add_u32_e32 v188, s92, v162
	s_addc_u32 s95, s76, s95
	v_ashrrev_i32_e32 v227, 31, v226
	v_ashrrev_i32_e32 v189, 31, v188
	v_lshl_add_u64 v[226:227], v[226:227], 2, s[94:95]
	v_lshl_add_u64 v[188:189], v[188:189], 2, s[12:13]
	global_load_dwordx4 v[218:221], v[226:227], off offset:16
	global_load_dwordx4 v[222:225], v[226:227], off
	global_load_dwordx4 v[230:233], v[226:227], off offset:528
	global_load_dwordx4 v[238:241], v[226:227], off offset:512
.Lpf_skip:
	s_cmp_eq_u32 s89, 0
	s_cbranch_scc1 .Lru_c0
	s_nop 0
	s_nop 0
	s_nop 0
	s_nop 1
	s_nop 1
	s_nop 0
	v_mov_b32_e32 v174, v242
	s_branch .Lru_j0
.Lru_c0:
	v_fmamk_f32 v173, v173, 0x3a800000, v228
	v_cmp_gt_f32_e32 vcc, s1, v173
	v_mul_f32_e32 v174, 0x4f800000, v173
	s_nop 0
	v_cndmask_b32_e32 v173, v173, v174, vcc
	v_sqrt_f32_e32 v174, v173
	s_nop 0
	v_add_u32_e32 v175, -1, v174
	v_fma_f32 v178, -v175, v174, v173
	v_cmp_ge_f32_e64 s[8:9], 0, v178
	v_add_u32_e32 v178, 1, v174
	s_nop 0
	v_cndmask_b32_e64 v175, v174, v175, s[8:9]
	v_fma_f32 v174, -v178, v174, v173
	v_cmp_lt_f32_e64 s[8:9], 0, v174
	s_nop 1
	v_cndmask_b32_e64 v174, v175, v178, s[8:9]
	v_mul_f32_e32 v175, 0x37800000, v174
	v_cndmask_b32_e32 v174, v174, v175, vcc
	v_cmp_class_f32_e32 vcc, v173, v229
	s_nop 1
	v_cndmask_b32_e32 v173, v174, v173, vcc
	v_div_scale_f32 v174, s[8:9], v173, v173, 1.0
	v_rcp_f32_e32 v175, v174
	s_nop 0
	v_fma_f32 v178, -v174, v175, 1.0
	v_fmac_f32_e32 v175, v178, v175
	v_div_scale_f32 v178, vcc, 1.0, v173, 1.0
	v_mul_f32_e32 v179, v178, v175
	v_fma_f32 v180, -v174, v179, v178
	v_fmac_f32_e32 v179, v180, v175
	v_fma_f32 v174, -v174, v179, v178
	v_div_fmas_f32 v174, v174, v175, v179
	v_div_fixup_f32 v174, v174, v173, 1.0
	v_mov_b32_e32 v242, v174
.Lru_j0:
	v_pk_fma_f32 v[136:137], v[136:137], v[174:175], v[88:89] op_sel_hi:[1,0,1]
	v_pk_fma_f32 v[142:143], v[142:143], v[174:175], v[94:95] op_sel_hi:[1,0,1]
	v_pk_fma_f32 v[140:141], v[140:141], v[174:175], v[92:93] op_sel_hi:[1,0,1]
	v_pk_fma_f32 v[138:139], v[138:139], v[174:175], v[90:91] op_sel_hi:[1,0,1]
	v_max_f32_e32 v136, 0, v136
	v_max_f32_e32 v137, 0, v137
	v_max_f32_e32 v140, 0, v140
	v_max_f32_e32 v141, 0, v141
	v_pk_mul_f32 v[178:179], v[136:137], v[136:137]
	v_max_f32_e32 v136, 0, v142
	v_max_f32_e32 v138, 0, v138
	v_max_f32_e32 v137, 0, v143
	v_max_f32_e32 v139, 0, v139
	v_pk_mul_f32 v[140:141], v[140:141], v[140:141]
	v_pk_mul_f32 v[142:143], v[136:137], v[136:137]
	v_pk_mul_f32 v[180:181], v[138:139], v[138:139]
	v_pk_fma_f32 v[128:129], v[128:129], v[174:175], v[80:81] op_sel_hi:[1,0,1]
	v_cvt_pk_bf16_f32 v136, v140, v141
	v_cvt_pk_bf16_f32 v137, v142, v143
	v_cvt_pk_bf16_f32 v138, v178, v179
	v_cvt_pk_bf16_f32 v139, v180, v181
	v_pk_fma_f32 v[134:135], v[134:135], v[174:175], v[86:87] op_sel_hi:[1,0,1]
	v_pk_fma_f32 v[132:133], v[132:133], v[174:175], v[84:85] op_sel_hi:[1,0,1]
	v_pk_fma_f32 v[130:131], v[130:131], v[174:175], v[82:83] op_sel_hi:[1,0,1]
	v_max_f32_e32 v128, 0, v128
	v_max_f32_e32 v129, 0, v129
	global_store_dwordx4 v[154:155], v[136:139], off
	v_max_f32_e32 v132, 0, v132
	v_max_f32_e32 v133, 0, v133
	v_pk_mul_f32 v[136:137], v[128:129], v[128:129]
	v_max_f32_e32 v128, 0, v134
	v_max_f32_e32 v130, 0, v130
	v_max_f32_e32 v129, 0, v135
	v_max_f32_e32 v131, 0, v131
	v_pk_mul_f32 v[132:133], v[132:133], v[132:133]
	v_pk_mul_f32 v[134:135], v[128:129], v[128:129]
	v_pk_mul_f32 v[138:139], v[130:131], v[130:131]
	v_cvt_pk_bf16_f32 v128, v132, v133
	v_cvt_pk_bf16_f32 v129, v134, v135
	v_cvt_pk_bf16_f32 v130, v136, v137
	v_cvt_pk_bf16_f32 v131, v138, v139
	global_store_dwordx4 v[154:155], v[128:131], off offset:256
	s_nop 1
	s_cmp_eq_u32 s89, 0
	s_cbranch_scc1 .Lru_c1
	v_lshlrev_b64 v[128:129], 13, v[176:177]
	v_lshl_add_u64 v[128:129], s[14:15], 0, v[128:129]
	v_lshl_add_u64 v[128:129], v[128:129], 0, v[158:159]
	s_nop 0
	s_nop 1
	s_nop 1
	s_nop 0
	v_mov_b32_e32 v130, v243
	s_branch .Lru_j1
.Lru_c1:
	v_fmamk_f32 v130, v172, 0x3a800000, v228
	v_cmp_gt_f32_e32 vcc, s1, v130
	v_mul_f32_e32 v131, 0x4f800000, v130
	v_lshlrev_b64 v[128:129], 13, v[176:177]
	v_cndmask_b32_e32 v130, v130, v131, vcc
	v_sqrt_f32_e32 v131, v130
	v_lshl_add_u64 v[128:129], s[14:15], 0, v[128:129]
	v_lshl_add_u64 v[128:129], v[128:129], 0, v[158:159]
	v_add_u32_e32 v132, -1, v131
	v_fma_f32 v133, -v132, v131, v130
	v_cmp_ge_f32_e64 s[8:9], 0, v133
	v_add_u32_e32 v133, 1, v131
	s_nop 0
	v_cndmask_b32_e64 v132, v131, v132, s[8:9]
	v_fma_f32 v131, -v133, v131, v130
	v_cmp_lt_f32_e64 s[8:9], 0, v131
	s_nop 1
	v_cndmask_b32_e64 v131, v132, v133, s[8:9]
	v_mul_f32_e32 v132, 0x37800000, v131
	v_cndmask_b32_e32 v131, v131, v132, vcc
	v_cmp_class_f32_e32 vcc, v130, v229
	s_nop 1
	v_cndmask_b32_e32 v130, v131, v130, vcc
	v_div_scale_f32 v131, s[8:9], v130, v130, 1.0
	v_rcp_f32_e32 v132, v131
	s_nop 0
	v_fma_f32 v133, -v131, v132, 1.0
	v_fmac_f32_e32 v132, v133, v132
	v_div_scale_f32 v133, vcc, 1.0, v130, 1.0
	v_mul_f32_e32 v134, v133, v132
	v_fma_f32 v135, -v131, v134, v133
	v_fmac_f32_e32 v134, v135, v132
	v_fma_f32 v131, -v131, v134, v133
	v_div_fmas_f32 v131, v131, v132, v134
	v_div_fixup_f32 v130, v131, v130, 1.0
	v_mov_b32_e32 v243, v130
.Lru_j1:
	v_pk_fma_f32 v[120:121], v[120:121], v[130:131], v[88:89] op_sel_hi:[1,0,1]
	v_pk_fma_f32 v[126:127], v[126:127], v[130:131], v[94:95] op_sel_hi:[1,0,1]
	v_pk_fma_f32 v[124:125], v[124:125], v[130:131], v[92:93] op_sel_hi:[1,0,1]
	v_pk_fma_f32 v[122:123], v[122:123], v[130:131], v[90:91] op_sel_hi:[1,0,1]
	v_max_f32_e32 v120, 0, v120
	v_max_f32_e32 v121, 0, v121
	v_max_f32_e32 v124, 0, v124
	v_max_f32_e32 v125, 0, v125
	v_pk_mul_f32 v[132:133], v[120:121], v[120:121]
	v_max_f32_e32 v120, 0, v126
	v_max_f32_e32 v122, 0, v122
	v_max_f32_e32 v121, 0, v127
	v_max_f32_e32 v123, 0, v123
	v_pk_mul_f32 v[124:125], v[124:125], v[124:125]
	v_pk_mul_f32 v[126:127], v[120:121], v[120:121]
	v_pk_mul_f32 v[134:135], v[122:123], v[122:123]
	v_pk_fma_f32 v[112:113], v[112:113], v[130:131], v[80:81] op_sel_hi:[1,0,1]
	v_cvt_pk_bf16_f32 v120, v124, v125
	v_cvt_pk_bf16_f32 v121, v126, v127
	v_cvt_pk_bf16_f32 v122, v132, v133
	v_cvt_pk_bf16_f32 v123, v134, v135
	v_pk_fma_f32 v[118:119], v[118:119], v[130:131], v[86:87] op_sel_hi:[1,0,1]
	v_pk_fma_f32 v[116:117], v[116:117], v[130:131], v[84:85] op_sel_hi:[1,0,1]
	v_pk_fma_f32 v[114:115], v[114:115], v[130:131], v[82:83] op_sel_hi:[1,0,1]
	v_max_f32_e32 v112, 0, v112
	v_max_f32_e32 v113, 0, v113
	global_store_dwordx4 v[128:129], v[120:123], off
	v_max_f32_e32 v116, 0, v116
	v_max_f32_e32 v117, 0, v117
	v_pk_mul_f32 v[120:121], v[112:113], v[112:113]
	v_max_f32_e32 v112, 0, v118
	v_max_f32_e32 v114, 0, v114
	v_max_f32_e32 v113, 0, v119
	v_max_f32_e32 v115, 0, v115
	v_pk_mul_f32 v[116:117], v[116:117], v[116:117]
	v_pk_mul_f32 v[118:119], v[112:113], v[112:113]
	v_pk_mul_f32 v[122:123], v[114:115], v[114:115]
	v_cvt_pk_bf16_f32 v112, v116, v117
	v_cvt_pk_bf16_f32 v113, v118, v119
	v_cvt_pk_bf16_f32 v114, v120, v121
	v_cvt_pk_bf16_f32 v115, v122, v123
	global_store_dwordx4 v[128:129], v[112:115], off offset:256
	s_nop 1
	s_cmp_eq_u32 s89, 0
	s_cbranch_scc1 .Lru_c2
	v_lshlrev_b64 v[112:113], 13, v[160:161]
	v_lshl_add_u64 v[112:113], s[14:15], 0, v[112:113]
	v_lshl_add_u64 v[112:113], v[112:113], 0, v[158:159]
	s_nop 0
	s_nop 1
	s_nop 1
	s_nop 0
	v_mov_b32_e32 v114, v244
	s_branch .Lru_j2
.Lru_c2:
	v_fmamk_f32 v114, v171, 0x3a800000, v228
	v_cmp_gt_f32_e32 vcc, s1, v114
	v_mul_f32_e32 v115, 0x4f800000, v114
	v_lshlrev_b64 v[112:113], 13, v[160:161]
	v_cndmask_b32_e32 v114, v114, v115, vcc
	v_sqrt_f32_e32 v115, v114
	v_lshl_add_u64 v[112:113], s[14:15], 0, v[112:113]
	v_lshl_add_u64 v[112:113], v[112:113], 0, v[158:159]
	v_add_u32_e32 v116, -1, v115
	v_fma_f32 v117, -v116, v115, v114
	v_cmp_ge_f32_e64 s[8:9], 0, v117
	v_add_u32_e32 v117, 1, v115
	s_nop 0
	v_cndmask_b32_e64 v116, v115, v116, s[8:9]
	v_fma_f32 v115, -v117, v115, v114
	v_cmp_lt_f32_e64 s[8:9], 0, v115
	s_nop 1
	v_cndmask_b32_e64 v115, v116, v117, s[8:9]
	v_mul_f32_e32 v116, 0x37800000, v115
	v_cndmask_b32_e32 v115, v115, v116, vcc
	v_cmp_class_f32_e32 vcc, v114, v229
	s_nop 1
	v_cndmask_b32_e32 v114, v115, v114, vcc
	v_div_scale_f32 v115, s[8:9], v114, v114, 1.0
	v_rcp_f32_e32 v116, v115
	s_nop 0
	v_fma_f32 v117, -v115, v116, 1.0
	v_fmac_f32_e32 v116, v117, v116
	v_div_scale_f32 v117, vcc, 1.0, v114, 1.0
	v_mul_f32_e32 v118, v117, v116
	v_fma_f32 v119, -v115, v118, v117
	v_fmac_f32_e32 v118, v119, v116
	v_fma_f32 v115, -v115, v118, v117
	v_div_fmas_f32 v115, v115, v116, v118
	v_div_fixup_f32 v114, v115, v114, 1.0
	v_mov_b32_e32 v244, v114
.Lru_j2:
	v_pk_fma_f32 v[104:105], v[104:105], v[114:115], v[88:89] op_sel_hi:[1,0,1]
	v_pk_fma_f32 v[110:111], v[110:111], v[114:115], v[94:95] op_sel_hi:[1,0,1]
	v_pk_fma_f32 v[108:109], v[108:109], v[114:115], v[92:93] op_sel_hi:[1,0,1]
	v_pk_fma_f32 v[106:107], v[106:107], v[114:115], v[90:91] op_sel_hi:[1,0,1]
	v_max_f32_e32 v104, 0, v104
	v_max_f32_e32 v105, 0, v105
	v_max_f32_e32 v108, 0, v108
	v_max_f32_e32 v109, 0, v109
	v_pk_mul_f32 v[116:117], v[104:105], v[104:105]
	v_max_f32_e32 v104, 0, v110
	v_max_f32_e32 v106, 0, v106
	v_max_f32_e32 v105, 0, v111
	v_max_f32_e32 v107, 0, v107
	v_pk_mul_f32 v[108:109], v[108:109], v[108:109]
	v_pk_mul_f32 v[110:111], v[104:105], v[104:105]
	v_pk_mul_f32 v[118:119], v[106:107], v[106:107]
	v_pk_fma_f32 v[96:97], v[96:97], v[114:115], v[80:81] op_sel_hi:[1,0,1]
	v_cvt_pk_bf16_f32 v104, v108, v109
	v_cvt_pk_bf16_f32 v105, v110, v111
	v_cvt_pk_bf16_f32 v106, v116, v117
	v_cvt_pk_bf16_f32 v107, v118, v119
	v_pk_fma_f32 v[102:103], v[102:103], v[114:115], v[86:87] op_sel_hi:[1,0,1]
	v_pk_fma_f32 v[100:101], v[100:101], v[114:115], v[84:85] op_sel_hi:[1,0,1]
	v_pk_fma_f32 v[98:99], v[98:99], v[114:115], v[82:83] op_sel_hi:[1,0,1]
	v_max_f32_e32 v96, 0, v96
	v_max_f32_e32 v97, 0, v97
	global_store_dwordx4 v[112:113], v[104:107], off
	v_max_f32_e32 v100, 0, v100
	v_max_f32_e32 v101, 0, v101
	v_pk_mul_f32 v[104:105], v[96:97], v[96:97]
	v_max_f32_e32 v96, 0, v102
	v_max_f32_e32 v98, 0, v98
	v_max_f32_e32 v97, 0, v103
	v_max_f32_e32 v99, 0, v99
	v_pk_mul_f32 v[100:101], v[100:101], v[100:101]
	v_pk_mul_f32 v[102:103], v[96:97], v[96:97]
	v_pk_mul_f32 v[106:107], v[98:99], v[98:99]
	v_cvt_pk_bf16_f32 v96, v100, v101
	v_cvt_pk_bf16_f32 v97, v102, v103
	v_cvt_pk_bf16_f32 v98, v104, v105
	v_cvt_pk_bf16_f32 v99, v106, v107
	global_store_dwordx4 v[112:113], v[96:99], off offset:256
	s_nop 1
	s_cmp_eq_u32 s89, 0
	s_cbranch_scc1 .Lru_c3
	v_lshlrev_b64 v[96:97], 13, v[156:157]
	v_lshl_add_u64 v[96:97], s[14:15], 0, v[96:97]
	v_lshl_add_u64 v[96:97], v[96:97], 0, v[158:159]
	s_nop 0
	s_nop 1
	s_nop 1
	s_mov_b64 s[8:9], 0x100000
	v_mov_b32_e32 v98, v245
	s_branch .Lru_j3
.Lru_c3:
	v_fmamk_f32 v98, v170, 0x3a800000, v228
	v_cmp_gt_f32_e32 vcc, s1, v98
	v_mul_f32_e32 v99, 0x4f800000, v98
	v_lshlrev_b64 v[96:97], 13, v[156:157]
	v_cndmask_b32_e32 v98, v98, v99, vcc
	v_sqrt_f32_e32 v99, v98
	v_lshl_add_u64 v[96:97], s[14:15], 0, v[96:97]
	v_lshl_add_u64 v[96:97], v[96:97], 0, v[158:159]
	v_add_u32_e32 v100, -1, v99
	v_fma_f32 v101, -v100, v99, v98
	v_cmp_ge_f32_e64 s[8:9], 0, v101
	v_add_u32_e32 v101, 1, v99
	s_nop 0
	v_cndmask_b32_e64 v100, v99, v100, s[8:9]
	v_fma_f32 v99, -v101, v99, v98
	v_cmp_lt_f32_e64 s[8:9], 0, v99
	s_nop 1
	v_cndmask_b32_e64 v99, v100, v101, s[8:9]
	v_mul_f32_e32 v100, 0x37800000, v99
	v_cndmask_b32_e32 v99, v99, v100, vcc
	v_cmp_class_f32_e32 vcc, v98, v229
	s_nop 1
	v_cndmask_b32_e32 v98, v99, v98, vcc
	v_div_scale_f32 v99, s[8:9], v98, v98, 1.0
	v_rcp_f32_e32 v100, v99
	s_mov_b64 s[8:9], 0x100000
	v_fma_f32 v101, -v99, v100, 1.0
	v_fmac_f32_e32 v100, v101, v100
	v_div_scale_f32 v101, vcc, 1.0, v98, 1.0
	v_mul_f32_e32 v102, v101, v100
	v_fma_f32 v103, -v99, v102, v101
	v_fmac_f32_e32 v102, v103, v100
	v_fma_f32 v99, -v99, v102, v101
	v_div_fmas_f32 v99, v99, v100, v102
	v_div_fixup_f32 v98, v99, v98, 1.0
	v_mov_b32_e32 v245, v98
.Lru_j3:
	v_pk_fma_f32 v[72:73], v[72:73], v[98:99], v[88:89] op_sel_hi:[1,0,1]
	v_pk_fma_f32 v[78:79], v[78:79], v[98:99], v[94:95] op_sel_hi:[1,0,1]
	v_pk_fma_f32 v[76:77], v[76:77], v[98:99], v[92:93] op_sel_hi:[1,0,1]
	v_pk_fma_f32 v[74:75], v[74:75], v[98:99], v[90:91] op_sel_hi:[1,0,1]
	v_max_f32_e32 v72, 0, v72
	v_max_f32_e32 v73, 0, v73
	v_max_f32_e32 v76, 0, v76
	v_max_f32_e32 v77, 0, v77
	v_pk_mul_f32 v[100:101], v[72:73], v[72:73]
	v_max_f32_e32 v72, 0, v78
	v_max_f32_e32 v74, 0, v74
	v_max_f32_e32 v73, 0, v79
	v_max_f32_e32 v75, 0, v75
	v_pk_mul_f32 v[76:77], v[76:77], v[76:77]
	v_pk_mul_f32 v[78:79], v[72:73], v[72:73]
	v_pk_mul_f32 v[102:103], v[74:75], v[74:75]
	v_pk_fma_f32 v[64:65], v[64:65], v[98:99], v[80:81] op_sel_hi:[1,0,1]
	v_cvt_pk_bf16_f32 v72, v76, v77
	v_cvt_pk_bf16_f32 v73, v78, v79
	v_cvt_pk_bf16_f32 v74, v100, v101
	v_cvt_pk_bf16_f32 v75, v102, v103
	v_pk_fma_f32 v[70:71], v[70:71], v[98:99], v[86:87] op_sel_hi:[1,0,1]
	v_pk_fma_f32 v[68:69], v[68:69], v[98:99], v[84:85] op_sel_hi:[1,0,1]
	v_pk_fma_f32 v[66:67], v[66:67], v[98:99], v[82:83] op_sel_hi:[1,0,1]
	v_max_f32_e32 v64, 0, v64
	v_max_f32_e32 v65, 0, v65
	global_store_dwordx4 v[96:97], v[72:75], off
	v_max_f32_e32 v68, 0, v68
	v_max_f32_e32 v69, 0, v69
	v_pk_mul_f32 v[72:73], v[64:65], v[64:65]
	v_max_f32_e32 v64, 0, v70
	v_max_f32_e32 v66, 0, v66
	v_max_f32_e32 v65, 0, v71
	v_max_f32_e32 v67, 0, v67
	v_pk_mul_f32 v[68:69], v[68:69], v[68:69]
	v_pk_mul_f32 v[70:71], v[64:65], v[64:65]
	v_pk_mul_f32 v[74:75], v[66:67], v[66:67]
	v_cvt_pk_bf16_f32 v64, v68, v69
	v_cvt_pk_bf16_f32 v65, v70, v71
	v_cvt_pk_bf16_f32 v66, v72, v73
	v_cvt_pk_bf16_f32 v67, v74, v75
	global_store_dwordx4 v[96:97], v[64:67], off offset:256
	s_nop 1
	s_cmp_eq_u32 s89, 0
	s_cbranch_scc1 .Lru_c4
	v_lshl_add_u64 v[64:65], v[154:155], 0, s[8:9]
	s_nop 0
	s_nop 0
	s_nop 1
	s_nop 1
	s_mov_b32 s8, 0x100000
	v_mov_b32_e32 v66, v246
	s_branch .Lru_j4
.Lru_c4:
	v_fmamk_f32 v66, v169, 0x3a800000, v228
	v_cmp_gt_f32_e32 vcc, s1, v66
	v_mul_f32_e32 v67, 0x4f800000, v66
	v_lshl_add_u64 v[64:65], v[154:155], 0, s[8:9]
	v_cndmask_b32_e32 v66, v66, v67, vcc
	v_sqrt_f32_e32 v67, v66
	s_nop 0
	v_add_u32_e32 v68, -1, v67
	v_fma_f32 v69, -v68, v67, v66
	v_cmp_ge_f32_e64 s[8:9], 0, v69
	v_add_u32_e32 v69, 1, v67
	s_nop 0
	v_cndmask_b32_e64 v68, v67, v68, s[8:9]
	v_fma_f32 v67, -v69, v67, v66
	v_cmp_lt_f32_e64 s[8:9], 0, v67
	s_nop 1
	v_cndmask_b32_e64 v67, v68, v69, s[8:9]
	v_mul_f32_e32 v68, 0x37800000, v67
	v_cndmask_b32_e32 v67, v67, v68, vcc
	v_cmp_class_f32_e32 vcc, v66, v229
	s_nop 1
	v_cndmask_b32_e32 v66, v67, v66, vcc
	v_div_scale_f32 v67, s[8:9], v66, v66, 1.0
	v_rcp_f32_e32 v68, v67
	s_mov_b32 s8, 0x100000
	v_fma_f32 v69, -v67, v68, 1.0
	v_fmac_f32_e32 v68, v69, v68
	v_div_scale_f32 v69, vcc, 1.0, v66, 1.0
	v_mul_f32_e32 v70, v69, v68
	v_fma_f32 v71, -v67, v70, v69
	v_fmac_f32_e32 v70, v71, v68
	v_fma_f32 v67, -v67, v70, v69
	v_div_fmas_f32 v67, v67, v68, v70
	v_div_fixup_f32 v66, v67, v66, 1.0
	v_mov_b32_e32 v246, v66
.Lru_j4:
	v_pk_fma_f32 v[60:61], v[60:61], v[66:67], v[92:93] op_sel_hi:[1,0,1]
	v_pk_fma_f32 v[56:57], v[56:57], v[66:67], v[88:89] op_sel_hi:[1,0,1]
	v_pk_fma_f32 v[62:63], v[62:63], v[66:67], v[94:95] op_sel_hi:[1,0,1]
	v_pk_fma_f32 v[58:59], v[58:59], v[66:67], v[90:91] op_sel_hi:[1,0,1]
	v_max_f32_e32 v60, 0, v60
	v_max_f32_e32 v56, 0, v56
	v_max_f32_e32 v61, 0, v61
	v_max_f32_e32 v57, 0, v57
	v_pk_mul_f32 v[60:61], v[60:61], v[60:61]
	v_pk_mul_f32 v[68:69], v[56:57], v[56:57]
	v_max_f32_e32 v56, 0, v62
	v_max_f32_e32 v58, 0, v58
	v_max_f32_e32 v57, 0, v63
	v_max_f32_e32 v59, 0, v59
	v_pk_mul_f32 v[62:63], v[56:57], v[56:57]
	v_pk_mul_f32 v[70:71], v[58:59], v[58:59]
	v_cvt_pk_bf16_f32 v56, v60, v61
	v_add_co_u32_e32 v60, vcc, s8, v154
	v_pk_fma_f32 v[48:49], v[48:49], v[66:67], v[80:81] op_sel_hi:[1,0,1]
	v_cvt_pk_bf16_f32 v57, v62, v63
	v_cvt_pk_bf16_f32 v58, v68, v69
	v_cvt_pk_bf16_f32 v59, v70, v71
	v_addc_co_u32_e32 v61, vcc, 0, v155, vcc
	v_pk_fma_f32 v[54:55], v[54:55], v[66:67], v[86:87] op_sel_hi:[1,0,1]
	v_pk_fma_f32 v[52:53], v[52:53], v[66:67], v[84:85] op_sel_hi:[1,0,1]
	v_pk_fma_f32 v[50:51], v[50:51], v[66:67], v[82:83] op_sel_hi:[1,0,1]
	v_max_f32_e32 v48, 0, v48
	v_max_f32_e32 v49, 0, v49
	global_store_dwordx4 v[60:61], v[56:59], off
	v_max_f32_e32 v52, 0, v52
	v_max_f32_e32 v53, 0, v53
	v_pk_mul_f32 v[56:57], v[48:49], v[48:49]
	v_max_f32_e32 v48, 0, v54
	v_max_f32_e32 v50, 0, v50
	v_max_f32_e32 v49, 0, v55
	v_max_f32_e32 v51, 0, v51
	v_pk_mul_f32 v[52:53], v[52:53], v[52:53]
	v_pk_mul_f32 v[54:55], v[48:49], v[48:49]
	v_pk_mul_f32 v[58:59], v[50:51], v[50:51]
	v_cvt_pk_bf16_f32 v48, v52, v53
	v_cvt_pk_bf16_f32 v49, v54, v55
	v_cvt_pk_bf16_f32 v50, v56, v57
	v_cvt_pk_bf16_f32 v51, v58, v59
	global_store_dwordx4 v[64:65], v[48:51], off offset:256
	s_mov_b64 s[8:9], 0x120000
	s_nop 0
	s_cmp_eq_u32 s89, 0
	s_cbranch_scc1 .Lru_c5
	v_lshl_add_u64 v[48:49], v[154:155], 0, s[8:9]
	s_nop 0
	s_nop 0
	s_nop 1
	s_nop 1
	s_mov_b32 s8, 0x120000
	v_mov_b32_e32 v50, v247
	s_branch .Lru_j5
.Lru_c5:
	v_fmamk_f32 v50, v168, 0x3a800000, v228
	v_cmp_gt_f32_e32 vcc, s1, v50
	v_mul_f32_e32 v51, 0x4f800000, v50
	v_lshl_add_u64 v[48:49], v[154:155], 0, s[8:9]
	v_cndmask_b32_e32 v50, v50, v51, vcc
	v_sqrt_f32_e32 v51, v50
	s_nop 0
	v_add_u32_e32 v52, -1, v51
	v_fma_f32 v53, -v52, v51, v50
	v_cmp_ge_f32_e64 s[8:9], 0, v53
	v_add_u32_e32 v53, 1, v51
	s_nop 0
	v_cndmask_b32_e64 v52, v51, v52, s[8:9]
	v_fma_f32 v51, -v53, v51, v50
	v_cmp_lt_f32_e64 s[8:9], 0, v51
	s_nop 1
	v_cndmask_b32_e64 v51, v52, v53, s[8:9]
	v_mul_f32_e32 v52, 0x37800000, v51
	v_cndmask_b32_e32 v51, v51, v52, vcc
	v_cmp_class_f32_e32 vcc, v50, v229
	s_nop 1
	v_cndmask_b32_e32 v50, v51, v50, vcc
	v_div_scale_f32 v51, s[8:9], v50, v50, 1.0
	v_rcp_f32_e32 v52, v51
	s_mov_b32 s8, 0x120000
	v_fma_f32 v53, -v51, v52, 1.0
	v_fmac_f32_e32 v52, v53, v52
	v_div_scale_f32 v53, vcc, 1.0, v50, 1.0
	v_mul_f32_e32 v54, v53, v52
	v_fma_f32 v55, -v51, v54, v53
	v_fmac_f32_e32 v54, v55, v52
	v_fma_f32 v51, -v51, v54, v53
	v_div_fmas_f32 v51, v51, v52, v54
	v_div_fixup_f32 v50, v51, v50, 1.0
	v_mov_b32_e32 v247, v50
.Lru_j5:
	v_pk_fma_f32 v[44:45], v[44:45], v[50:51], v[92:93] op_sel_hi:[1,0,1]
	v_pk_fma_f32 v[40:41], v[40:41], v[50:51], v[88:89] op_sel_hi:[1,0,1]
	v_pk_fma_f32 v[46:47], v[46:47], v[50:51], v[94:95] op_sel_hi:[1,0,1]
	v_pk_fma_f32 v[42:43], v[42:43], v[50:51], v[90:91] op_sel_hi:[1,0,1]
	v_max_f32_e32 v44, 0, v44
	v_max_f32_e32 v40, 0, v40
	v_max_f32_e32 v45, 0, v45
	v_max_f32_e32 v41, 0, v41
	v_pk_mul_f32 v[44:45], v[44:45], v[44:45]
	v_pk_mul_f32 v[52:53], v[40:41], v[40:41]
	v_max_f32_e32 v40, 0, v46
	v_max_f32_e32 v42, 0, v42
	v_max_f32_e32 v41, 0, v47
	v_max_f32_e32 v43, 0, v43
	v_pk_mul_f32 v[46:47], v[40:41], v[40:41]
	v_pk_mul_f32 v[54:55], v[42:43], v[42:43]
	v_cvt_pk_bf16_f32 v40, v44, v45
	v_add_co_u32_e32 v44, vcc, s8, v154
	v_pk_fma_f32 v[32:33], v[32:33], v[50:51], v[80:81] op_sel_hi:[1,0,1]
	v_cvt_pk_bf16_f32 v41, v46, v47
	v_cvt_pk_bf16_f32 v42, v52, v53
	v_cvt_pk_bf16_f32 v43, v54, v55
	v_addc_co_u32_e32 v45, vcc, 0, v155, vcc
	v_pk_fma_f32 v[38:39], v[38:39], v[50:51], v[86:87] op_sel_hi:[1,0,1]
	v_pk_fma_f32 v[36:37], v[36:37], v[50:51], v[84:85] op_sel_hi:[1,0,1]
	v_pk_fma_f32 v[34:35], v[34:35], v[50:51], v[82:83] op_sel_hi:[1,0,1]
	v_max_f32_e32 v32, 0, v32
	v_max_f32_e32 v33, 0, v33
	global_store_dwordx4 v[44:45], v[40:43], off
	v_max_f32_e32 v36, 0, v36
	v_max_f32_e32 v37, 0, v37
	v_pk_mul_f32 v[40:41], v[32:33], v[32:33]
	v_max_f32_e32 v32, 0, v38
	v_max_f32_e32 v34, 0, v34
	v_max_f32_e32 v33, 0, v39
	v_max_f32_e32 v35, 0, v35
	v_pk_mul_f32 v[36:37], v[36:37], v[36:37]
	v_pk_mul_f32 v[38:39], v[32:33], v[32:33]
	v_pk_mul_f32 v[42:43], v[34:35], v[34:35]
	v_cvt_pk_bf16_f32 v32, v36, v37
	v_cvt_pk_bf16_f32 v33, v38, v39
	v_cvt_pk_bf16_f32 v34, v40, v41
	v_cvt_pk_bf16_f32 v35, v42, v43
	global_store_dwordx4 v[48:49], v[32:35], off offset:256
	s_mov_b64 s[8:9], 0x140000
	s_nop 0
	s_cmp_eq_u32 s89, 0
	s_cbranch_scc1 .Lru_c6
	v_lshl_add_u64 v[32:33], v[154:155], 0, s[8:9]
	s_nop 0
	s_nop 0
	s_nop 1
	s_nop 1
	s_mov_b32 s8, 0x140000
	v_mov_b32_e32 v34, v248
	s_branch .Lru_j6
.Lru_c6:
	v_fmamk_f32 v34, v167, 0x3a800000, v228
	v_cmp_gt_f32_e32 vcc, s1, v34
	v_mul_f32_e32 v35, 0x4f800000, v34
	v_lshl_add_u64 v[32:33], v[154:155], 0, s[8:9]
	v_cndmask_b32_e32 v34, v34, v35, vcc
	v_sqrt_f32_e32 v35, v34
	s_nop 0
	v_add_u32_e32 v36, -1, v35
	v_fma_f32 v37, -v36, v35, v34
	v_cmp_ge_f32_e64 s[8:9], 0, v37
	v_add_u32_e32 v37, 1, v35
	s_nop 0
	v_cndmask_b32_e64 v36, v35, v36, s[8:9]
	v_fma_f32 v35, -v37, v35, v34
	v_cmp_lt_f32_e64 s[8:9], 0, v35
	s_nop 1
	v_cndmask_b32_e64 v35, v36, v37, s[8:9]
	v_mul_f32_e32 v36, 0x37800000, v35
	v_cndmask_b32_e32 v35, v35, v36, vcc
	v_cmp_class_f32_e32 vcc, v34, v229
	s_nop 1
	v_cndmask_b32_e32 v34, v35, v34, vcc
	v_div_scale_f32 v35, s[8:9], v34, v34, 1.0
	v_rcp_f32_e32 v36, v35
	s_mov_b32 s8, 0x140000
	v_fma_f32 v37, -v35, v36, 1.0
	v_fmac_f32_e32 v36, v37, v36
	v_div_scale_f32 v37, vcc, 1.0, v34, 1.0
	v_mul_f32_e32 v38, v37, v36
	v_fma_f32 v39, -v35, v38, v37
	v_fmac_f32_e32 v38, v39, v36
	v_fma_f32 v35, -v35, v38, v37
	v_div_fmas_f32 v35, v35, v36, v38
	v_div_fixup_f32 v34, v35, v34, 1.0
	v_mov_b32_e32 v248, v34
.Lru_j6:
	v_pk_fma_f32 v[28:29], v[28:29], v[34:35], v[92:93] op_sel_hi:[1,0,1]
	v_pk_fma_f32 v[24:25], v[24:25], v[34:35], v[88:89] op_sel_hi:[1,0,1]
	v_pk_fma_f32 v[30:31], v[30:31], v[34:35], v[94:95] op_sel_hi:[1,0,1]
	v_pk_fma_f32 v[26:27], v[26:27], v[34:35], v[90:91] op_sel_hi:[1,0,1]
	v_max_f32_e32 v28, 0, v28
	v_max_f32_e32 v24, 0, v24
	v_max_f32_e32 v29, 0, v29
	v_max_f32_e32 v25, 0, v25
	v_pk_mul_f32 v[28:29], v[28:29], v[28:29]
	v_pk_mul_f32 v[36:37], v[24:25], v[24:25]
	v_max_f32_e32 v24, 0, v30
	v_max_f32_e32 v26, 0, v26
	v_max_f32_e32 v25, 0, v31
	v_max_f32_e32 v27, 0, v27
	v_pk_mul_f32 v[30:31], v[24:25], v[24:25]
	v_pk_mul_f32 v[38:39], v[26:27], v[26:27]
	v_cvt_pk_bf16_f32 v24, v28, v29
	v_add_co_u32_e32 v28, vcc, s8, v154
	v_pk_fma_f32 v[16:17], v[16:17], v[34:35], v[80:81] op_sel_hi:[1,0,1]
	v_cvt_pk_bf16_f32 v25, v30, v31
	v_cvt_pk_bf16_f32 v26, v36, v37
	v_cvt_pk_bf16_f32 v27, v38, v39
	v_addc_co_u32_e32 v29, vcc, 0, v155, vcc
	v_pk_fma_f32 v[22:23], v[22:23], v[34:35], v[86:87] op_sel_hi:[1,0,1]
	v_pk_fma_f32 v[20:21], v[20:21], v[34:35], v[84:85] op_sel_hi:[1,0,1]
	v_pk_fma_f32 v[18:19], v[18:19], v[34:35], v[82:83] op_sel_hi:[1,0,1]
	v_max_f32_e32 v16, 0, v16
	v_max_f32_e32 v17, 0, v17
	global_store_dwordx4 v[28:29], v[24:27], off
	v_max_f32_e32 v20, 0, v20
	v_max_f32_e32 v21, 0, v21
	v_pk_mul_f32 v[24:25], v[16:17], v[16:17]
	v_max_f32_e32 v16, 0, v22
	v_max_f32_e32 v18, 0, v18
	v_max_f32_e32 v17, 0, v23
	v_max_f32_e32 v19, 0, v19
	v_pk_mul_f32 v[20:21], v[20:21], v[20:21]
	v_pk_mul_f32 v[22:23], v[16:17], v[16:17]
	v_pk_mul_f32 v[26:27], v[18:19], v[18:19]
	v_cvt_pk_bf16_f32 v16, v20, v21
	v_cvt_pk_bf16_f32 v17, v22, v23
	v_cvt_pk_bf16_f32 v18, v24, v25
	v_cvt_pk_bf16_f32 v19, v26, v27
	global_store_dwordx4 v[32:33], v[16:19], off offset:256
	s_mov_b64 s[8:9], 0x160000
	s_nop 0
	s_cmp_eq_u32 s89, 0
	s_cbranch_scc1 .Lru_c7
	v_lshl_add_u64 v[16:17], v[154:155], 0, s[8:9]
	s_nop 0
	s_nop 0
	s_nop 1
	s_nop 1
	s_mov_b32 s8, 0x160000
	v_mov_b32_e32 v18, v249
	s_branch .Lru_j7
.Lru_c7:
	v_fmamk_f32 v18, v166, 0x3a800000, v228
	v_cmp_gt_f32_e32 vcc, s1, v18
	v_mul_f32_e32 v19, 0x4f800000, v18
	v_lshl_add_u64 v[16:17], v[154:155], 0, s[8:9]
	v_cndmask_b32_e32 v18, v18, v19, vcc
	v_sqrt_f32_e32 v19, v18
	s_nop 0
	v_add_u32_e32 v20, -1, v19
	v_fma_f32 v21, -v20, v19, v18
	v_cmp_ge_f32_e64 s[8:9], 0, v21
	v_add_u32_e32 v21, 1, v19
	s_nop 0
	v_cndmask_b32_e64 v20, v19, v20, s[8:9]
	v_fma_f32 v19, -v21, v19, v18
	v_cmp_lt_f32_e64 s[8:9], 0, v19
	s_nop 1
	v_cndmask_b32_e64 v19, v20, v21, s[8:9]
	v_mul_f32_e32 v20, 0x37800000, v19
	v_cndmask_b32_e32 v19, v19, v20, vcc
	v_cmp_class_f32_e32 vcc, v18, v229
	s_nop 1
	v_cndmask_b32_e32 v18, v19, v18, vcc
	v_div_scale_f32 v19, s[8:9], v18, v18, 1.0
	v_rcp_f32_e32 v20, v19
	s_mov_b32 s8, 0x160000
	v_fma_f32 v21, -v19, v20, 1.0
	v_fmac_f32_e32 v20, v21, v20
	v_div_scale_f32 v21, vcc, 1.0, v18, 1.0
	v_mul_f32_e32 v22, v21, v20
	v_fma_f32 v23, -v19, v22, v21
	v_fmac_f32_e32 v22, v23, v20
	v_fma_f32 v19, -v19, v22, v21
	v_div_fmas_f32 v19, v19, v20, v22
	v_div_fixup_f32 v18, v19, v18, 1.0
	v_mov_b32_e32 v249, v18
.Lru_j7:
	v_pk_fma_f32 v[12:13], v[12:13], v[18:19], v[92:93] op_sel_hi:[1,0,1]
	v_pk_fma_f32 v[8:9], v[8:9], v[18:19], v[88:89] op_sel_hi:[1,0,1]
	v_pk_fma_f32 v[14:15], v[14:15], v[18:19], v[94:95] op_sel_hi:[1,0,1]
	v_pk_fma_f32 v[10:11], v[10:11], v[18:19], v[90:91] op_sel_hi:[1,0,1]
	v_max_f32_e32 v12, 0, v12
	v_max_f32_e32 v8, 0, v8
	v_max_f32_e32 v13, 0, v13
	v_max_f32_e32 v9, 0, v9
	v_pk_mul_f32 v[12:13], v[12:13], v[12:13]
	v_pk_mul_f32 v[20:21], v[8:9], v[8:9]
	v_max_f32_e32 v8, 0, v14
	v_max_f32_e32 v10, 0, v10
	v_max_f32_e32 v9, 0, v15
	v_max_f32_e32 v11, 0, v11
	v_pk_mul_f32 v[14:15], v[8:9], v[8:9]
	v_pk_mul_f32 v[22:23], v[10:11], v[10:11]
	v_cvt_pk_bf16_f32 v8, v12, v13
	v_add_co_u32_e32 v12, vcc, s8, v154
	v_pk_fma_f32 v[0:1], v[0:1], v[18:19], v[80:81] op_sel_hi:[1,0,1]
	v_cvt_pk_bf16_f32 v9, v14, v15
	v_cvt_pk_bf16_f32 v10, v20, v21
	v_cvt_pk_bf16_f32 v11, v22, v23
	v_addc_co_u32_e32 v13, vcc, 0, v155, vcc
	v_pk_fma_f32 v[6:7], v[6:7], v[18:19], v[86:87] op_sel_hi:[1,0,1]
	v_pk_fma_f32 v[4:5], v[4:5], v[18:19], v[84:85] op_sel_hi:[1,0,1]
	v_pk_fma_f32 v[2:3], v[2:3], v[18:19], v[82:83] op_sel_hi:[1,0,1]
	v_max_f32_e32 v0, 0, v0
	v_max_f32_e32 v1, 0, v1
	global_store_dwordx4 v[12:13], v[8:11], off
	v_max_f32_e32 v4, 0, v4
	v_max_f32_e32 v5, 0, v5
	v_pk_mul_f32 v[8:9], v[0:1], v[0:1]
	v_max_f32_e32 v0, 0, v6
	v_max_f32_e32 v2, 0, v2
	v_max_f32_e32 v1, 0, v7
	v_max_f32_e32 v3, 0, v3
	v_pk_mul_f32 v[4:5], v[4:5], v[4:5]
	v_pk_mul_f32 v[6:7], v[0:1], v[0:1]
	v_pk_mul_f32 v[10:11], v[2:3], v[2:3]
	v_cvt_pk_bf16_f32 v0, v4, v5
	v_cvt_pk_bf16_f32 v1, v6, v7
	v_cvt_pk_bf16_f32 v2, v8, v9
	v_cvt_pk_bf16_f32 v3, v10, v11
	s_mov_b64 s[8:9], -1
	s_andn2_b64 vcc, exec, s[6:7]
	global_store_dwordx4 v[16:17], v[0:3], off offset:256
	s_mov_b32 s87, s40
	s_cbranch_vccnz .LBB0_1296
	s_andn2_b64 vcc, exec, s[10:11]
	s_cbranch_vccnz .LBB0_1295
	s_barrier
	s_branch .LBB0_1295
